# mnorm: every 8 tokens one load per array pulls the lines of the tokens 8..15 ahead into L2
# baseline (speedup 1.0000x reference)
; #define MN_LOAD(tk_) do { const int s_ = (tk_) & (SEQL - 1); hr = *(const u32x2*)(Hm + (size_t)(tk_) * 2048 + c); zr = *(const u32x2*)(Y0 + (size_t)(tk_) * 4096 + 2048 + c); \
;             _Pragma("unroll") for (int j = 0; j < 4; ++j) xr[j] = (s_ - 3 + j >= 0) ? *(const u32x2*)(XM + (size_t)((tk_) - 3 + j) * 2048 + c) : (u32x2){0u, 0u}; } while (0)
; __device__ void mnorm_phase(const Params& p) {
;     ...
;     for (int blk = blockIdx.x; blk < 256; blk += gridDim.x) {
;         u32x2 hr, xr[4], zr;
;     ...
;         MN_LOAD(blk * 64);
.LBB0_594:
	v_and_b32_e32 v102, 0x3ff, v0
	v_lshrrev_b32_e32 v103, 6, v102
	v_and_b32_e32 v102, 63, v102
	v_lshlrev_b32_e32 v103, 9, v103
	v_and_b32_e32 v100, 3, v102
	v_lshl_add_u32 v103, v100, 7, v103
	v_bfe_u32 v100, v102, 2, 3
	v_lshl_add_u32 v100, v100, 12, v103
	v_cmp_lt_u32_e32 vcc, 31, v102
	v_mov_b32_e32 v101, 0x8000000
	v_cndmask_b32_e32 v101, 0, v101, vcc
	v_add_u32_e32 v100, v100, v101
	v_lshrrev_b32_e32 v101, 2, v102
	v_lshl_add_u32 v101, v101, 13, v103
	v_add_u32_e32 v101, 0xc001000, v101
	s_lshl_b32 s30, s15, 6
	s_lshl_b32 s31, s30, 12
	s_lshl_b32 s32, s30, 13
	v_add_u32_e32 v102, s31, v100
	v_add_u32_e32 v103, s32, v101
	global_load_dword v104, v102, s[64:65]
	global_load_dword v104, v103, s[64:65]
	s_lshl_b32 s6, s15, 6
	s_ashr_i32 s7, s6, 31
	s_lshl_b64 s[2:3], s[6:7], 12
	s_lshl_b64 s[8:9], s[6:7], 13
	s_add_u32 s8, s10, s8
	s_addc_u32 s9, s12, s9
	s_waitcnt vmcnt(2)
	v_lshl_add_u64 v[48:49], s[8:9], 0, v[26:27]
	v_lshl_add_u64 v[52:53], v[30:31], 0, s[2:3]
	v_add_co_u32_e32 v54, vcc, 0x1000, v48
	s_and_b32 s16, s15, 63
	s_nop 0
	v_addc_co_u32_e32 v55, vcc, 0, v49, vcc
	global_load_dwordx2 v[50:51], v[52:53], off
	global_load_dwordx2 v[48:49], v[54:55], off
	s_cmp_lg_u32 s16, 0
	s_cselect_b64 s[8:9], -1, 0
	s_cmp_eq_u32 s16, 0
	v_lshl_add_u64 v[52:53], v[32:33], 0, s[2:3]
	s_cbranch_scc1 .LBB0_598
	v_add_co_u32_e32 v54, vcc, 0xffffd000, v52
	s_nop 1
	v_addc_co_u32_e32 v55, vcc, -1, v53, vcc
	global_load_dwordx2 v[56:57], v[54:55], off
	v_cndmask_b32_e64 v2, 0, 1, s[8:9]
	v_cmp_ne_u32_e64 s[2:3], 1, v2
	s_andn2_b64 vcc, exec, s[8:9]
	s_cbranch_vccnz .LBB0_599

; __device__ __forceinline__ unsigned pk2(float lo, float hi) { unsigned r; asm volatile("v_cvt_pk_bf16_f32 %0, %1, %2" : "=v"(r) : "v"(lo), "v"(hi)); return r; }
; __device__ __forceinline__ float bflo(unsigned w) { return __uint_as_float(w << 16); }
; __device__ __forceinline__ float bfhi(unsigned w) { return __uint_as_float(w & 0xffff0000u); }
; __device__ __forceinline__ float fsig0(float x) { return __builtin_amdgcn_rcpf(1.0f + __expf(-x)); }
; #define MN_LOAD(tk_) do { const int s_ = (tk_) & (SEQL - 1); hr = *(const u32x2*)(Hm + (size_t)(tk_) * 2048 + c); zr = *(const u32x2*)(Y0 + (size_t)(tk_) * 4096 + 2048 + c); \
;             _Pragma("unroll") for (int j = 0; j < 4; ++j) xr[j] = (s_ - 3 + j >= 0) ? *(const u32x2*)(XM + (size_t)((tk_) - 3 + j) * 2048 + c) : (u32x2){0u, 0u}; } while (0)
; __device__ void mnorm_phase(const Params& p) {
;     ...
;         for (int tt = 0; tt < 64; ++tt) {
;             const int tk = blk * 64 + tt;
;             const u32x2 hc_ = hr, zc_ = zr; const u32x2 xc0 = xr[0], xc1 = xr[1], xc2 = xr[2], xc3 = xr[3];
;             if (tt < 63) MN_LOAD(tk + 1);
;             float hv[4] = {bflo(hc_.x), bfhi(hc_.x), bflo(hc_.y), bfhi(hc_.y)};
;             const float mu = wave_sum_dpp(hv[0] + hv[1] + hv[2] + hv[3]) * (1.0f / 256.0f);
;             float d[4], sq = 0.f;
; #pragma unroll
;             for (int i = 0; i < 4; ++i) { d[i] = hv[i] - mu; sq += d[i] * d[i]; }
;             const float rs = rsqrtf(wave_sum_dpp(sq) * (1.0f / 256.0f) + 1e-6f);
;             float xmc[4] = {cbv[0], cbv[1], cbv[2], cbv[3]};
;             const u32x2 xs[4] = {xc0, xc1, xc2, xc3};
; #pragma unroll
;             for (int j = 0; j < 4; ++j) { xmc[0] += cw[j][0] * bflo(xs[j].x); xmc[1] += cw[j][1] * bfhi(xs[j].x); xmc[2] += cw[j][2] * bflo(xs[j].y); xmc[3] += cw[j][3] * bfhi(xs[j].y); }
;             const float z[4] = {bflo(zc_.x), bfhi(zc_.x), bflo(zc_.y), bfhi(zc_.y)};
;             float o[4];
; #pragma unroll
;             for (int i = 0; i < 4; ++i) o[i] = (d[i] * rs * gn[i] + skip[i] * xmc[i] * fsig0(xmc[i])) * z[i] * fsig0(z[i]);
;             u32x2 w; w.x = pk2(o[0], o[1]); w.y = pk2(o[2], o[3]); *(u32x2*)(Y0 + (size_t)tk * 4096 + 2048 + c) = w;
;         }
.LBB0_604:
	s_and_b32 s30, s8, 6
	s_cmp_eq_u32 s30, 0
	s_cbranch_scc0 MNPULL_skip
	s_add_i32 s30, s13, s8
	s_add_i32 s30, s30, 8
	s_lshl_b32 s31, s30, 12
	s_lshl_b32 s32, s30, 13
	v_add_u32_e32 v102, s31, v100
	v_add_u32_e32 v103, s32, v101
	global_load_dword v104, v102, s[64:65]
	global_load_dword v104, v103, s[64:65]
MNPULL_skip:
	v_lshlrev_b32_e32 v75, 16, v70
	v_and_b32_e32 v77, 0xffff0000, v70
	v_lshlrev_b32_e32 v81, 16, v71
	v_add_f32_e32 v2, v75, v77
	v_and_b32_e32 v71, 0xffff0000, v71
	v_add_f32_e32 v2, v2, v81
	v_add_f32_e32 v2, v2, v71
	v_and_b32_e32 v85, 0xffff0000, v66
	v_and_b32_e32 v84, 0xffff0000, v62
	v_add_f32_dpp v2, v2, v2 quad_perm:[1,0,3,2] row_mask:0xf bank_mask:0xf bound_ctrl:1
	v_and_b32_e32 v7, 0xffff0000, v69
	v_pk_mul_f32 v[84:85], v[14:15], v[84:85]
	v_add_f32_dpp v2, v2, v2 quad_perm:[2,3,0,1] row_mask:0xf bank_mask:0xf bound_ctrl:1
	v_mov_b32_e32 v86, v84
	v_lshlrev_b32_e32 v89, 16, v67
	v_add_f32_dpp v2, v2, v2 row_half_mirror row_mask:0xf bank_mask:0xf bound_ctrl:1
	v_lshlrev_b32_e32 v88, 16, v63
	v_mov_b32_e32 v28, v85
	v_add_f32_dpp v2, v2, v2 row_mirror row_mask:0xf bank_mask:0xf bound_ctrl:1
	v_pk_mul_f32 v[88:89], v[44:45], v[88:89]
	v_readlane_b32 s3, v2, 16
	v_readlane_b32 s2, v2, 0
	v_and_b32_e32 v67, 0xffff0000, v67
	v_mov_b32_e32 v4, s3
	v_add_f32_e32 v83, s2, v4
	v_readlane_b32 s2, v2, 32
	v_and_b32_e32 v4, 0xffff0000, v68
	v_readlane_b32 s3, v2, 48
	v_lshlrev_b32_e32 v2, 16, v68
	v_mul_f32_e32 v82, v19, v4
	v_lshlrev_b32_e32 v4, 16, v69
	v_lshlrev_b32_e32 v69, 16, v66
	v_lshlrev_b32_e32 v68, 16, v62
	v_mov_b32_e32 v43, s2
	v_fma_f32 v2, v18, v2, v10
	v_pk_mul_f32 v[68:69], v[46:47], v[68:69]
	v_pk_add_f32 v[82:83], v[42:43], v[82:83]
	v_mov_b32_e32 v87, s3
	v_fma_f32 v4, v20, v4, v12
	v_add_f32_e32 v2, v2, v68
	v_pk_add_f32 v[82:83], v[82:83], v[86:87]
	v_and_b32_e32 v66, 0xffff0000, v63
	v_fma_f32 v7, v21, v7, v13
	v_add_f32_e32 v68, v2, v69
	v_pk_mul_f32 v[86:87], v[82:83], v[28:29]
	v_add_f32_e32 v2, v4, v88
	v_pk_mul_f32 v[62:63], v[16:17], v[66:67]
	v_add_f32_e32 v86, v2, v89
	v_add_f32_e32 v2, v7, v62
	v_add_f32_e32 v62, v2, v63
	v_lshlrev_b32_e32 v2, 16, v64
	v_mul_f32_e32 v74, v22, v2
	v_and_b32_e32 v2, 0xffff0000, v64
	v_mul_f32_e32 v76, v23, v2
	v_lshlrev_b32_e32 v2, 16, v65
	v_mul_f32_e32 v80, v24, v2
	v_and_b32_e32 v2, 0xffff0000, v65
	v_lshlrev_b32_e32 v4, 16, v52
	v_mul_f32_e32 v70, v25, v2
	v_and_b32_e32 v9, 0xffff0000, v52
	v_mul_f32_e32 v2, 0xbfb8aa3b, v4
	v_exp_f32_e32 v2, v2
	v_mul_f32_e32 v7, 0xbfb8aa3b, v9
	v_exp_f32_e32 v7, v7
	v_lshlrev_b32_e32 v11, 16, v53
	v_add_f32_e32 v2, 1.0, v2
	v_and_b32_e32 v43, 0xffff0000, v53
	v_rcp_f32_e32 v37, v2
	v_add_f32_e32 v2, 1.0, v7
	v_pk_add_f32 v[52:53], v[80:81], v[86:87]
	v_rcp_f32_e32 v88, v2
	v_mul_f32_e32 v2, 0xbfb8aa3b, v52
	v_exp_f32_e32 v2, v2
	v_mul_f32_e32 v7, 0xbfb8aa3b, v11
	v_exp_f32_e32 v7, v7
	v_mov_b32_e32 v63, v87
	v_pk_add_f32 v[64:65], v[80:81], v[86:87] neg_lo:[0,1] neg_hi:[0,1]
	v_pk_add_f32 v[66:67], v[70:71], v[62:63]
	v_pk_add_f32 v[62:63], v[70:71], v[62:63] neg_lo:[0,1] neg_hi:[0,1]
	v_mov_b32_e32 v69, v87
	v_add_f32_e32 v2, 1.0, v2
	v_mov_b32_e32 v67, v63
	v_mov_b32_e32 v64, v63
	v_pk_add_f32 v[62:63], v[74:75], v[68:69]
	v_pk_fma_f32 v[68:69], v[82:83], v[28:29], v[74:75] neg_lo:[1,0,0] neg_hi:[1,0,0]
	v_rcp_f32_e32 v34, v2
	v_add_f32_e32 v2, 1.0, v7
	v_pk_fma_f32 v[74:75], v[82:83], v[28:29], v[76:77] neg_lo:[1,0,0] neg_hi:[1,0,0]
	v_mul_f32_e32 v7, v69, v69
	v_mov_b32_e32 v53, v65
	v_pk_mul_f32 v[64:65], v[64:65], v[64:65]
	v_fmac_f32_e32 v7, v75, v75
	v_add_f32_e32 v7, v65, v7
	v_add_f32_e32 v7, v64, v7
	v_pk_add_f32 v[84:85], v[82:83], v[28:29]
	v_rcp_f32_e32 v80, v2
	v_add_f32_dpp v7, v7, v7 quad_perm:[1,0,3,2] row_mask:0xf bank_mask:0xf bound_ctrl:1
	v_mul_f32_e32 v2, 0xbfb8aa3b, v62
	v_exp_f32_e32 v2, v2
	v_add_f32_dpp v7, v7, v7 quad_perm:[2,3,0,1] row_mask:0xf bank_mask:0xf bound_ctrl:1
	v_mov_b32_e32 v85, v87
	v_pk_add_f32 v[70:71], v[76:77], v[84:85]
	v_add_f32_dpp v7, v7, v7 row_half_mirror row_mask:0xf bank_mask:0xf bound_ctrl:1
	v_add_f32_e32 v2, 1.0, v2
	v_rcp_f32_e32 v38, v2
	v_add_f32_dpp v7, v7, v7 row_mirror row_mask:0xf bank_mask:0xf bound_ctrl:1
	v_mul_f32_e32 v2, 0xbfb8aa3b, v70
	v_readlane_b32 s3, v7, 16
	v_readlane_b32 s2, v7, 0
	v_exp_f32_e32 v2, v2
	v_mov_b32_e32 v28, s3
	v_add_f32_e32 v28, s2, v28
	v_readlane_b32 s2, v7, 32
	v_add_f32_e32 v2, 1.0, v2
	v_mov_b32_e32 v63, v69
	v_add_f32_e32 v28, s2, v28
	v_readlane_b32 s2, v7, 48
	v_rcp_f32_e32 v2, v2
	v_mov_b32_e32 v71, v75
	v_add_f32_e32 v7, s2, v28
	v_fmamk_f32 v7, v7, 0x3b800000, v79
	v_mul_f32_e32 v28, 0x4b800000, v7
	v_cmp_gt_f32_e32 vcc, s11, v7
	s_add_i32 s8, s8, 2
	v_lshl_add_u64 v[72:73], v[72:73], 0, s[4:5]
	v_cndmask_b32_e32 v7, v7, v28, vcc
	v_rsq_f32_e32 v7, v7
	s_cmp_eq_u32 s8, 64
	v_mul_f32_e32 v28, 0x45800000, v7
	v_cndmask_b32_e32 v7, v7, v28, vcc
	v_pk_mul_f32 v[62:63], v[6:7], v[62:63]
	v_mov_b32_e32 v41, v7
	v_pk_mul_f32 v[62:63], v[62:63], v[38:39]
	s_nop 0
	v_add_f32_e32 v28, v62, v63
	v_pk_mul_f32 v[62:63], v[40:41], v[70:71]
	v_mul_f32_e32 v4, v28, v4
	v_pk_mul_f32 v[62:63], v[62:63], v[2:3]
	v_mul_f32_e32 v28, v37, v4
	v_add_f32_e32 v2, v62, v63
	v_mul_f32_e32 v2, v2, v9
	v_mov_b32_e32 v9, v7
	v_pk_mul_f32 v[52:53], v[8:9], v[52:53]
	v_mov_b32_e32 v37, v7
	v_pk_mul_f32 v[52:53], v[52:53], v[34:35]
	v_mul_f32_e32 v7, 0xbfb8aa3b, v43
	v_add_f32_e32 v4, v52, v53
	v_mul_f32_e32 v4, v4, v11
	v_mul_f32_e32 v9, v80, v4
	v_mul_f32_e32 v4, 0xbfb8aa3b, v66
	v_exp_f32_e32 v4, v4
	v_exp_f32_e32 v7, v7
	v_pk_mul_f32 v[52:53], v[36:37], v[66:67]
	v_mul_f32_e32 v2, v88, v2
	v_add_f32_e32 v4, 1.0, v4
	v_rcp_f32_e32 v4, v4
	v_add_f32_e32 v7, 1.0, v7
	v_rcp_f32_e32 v7, v7
	v_pk_mul_f32 v[52:53], v[52:53], v[4:5]
	s_nop 0
	v_add_f32_e32 v4, v52, v53
	v_mul_f32_e32 v4, v4, v43
	v_mul_f32_e32 v4, v7, v4
	v_cvt_pk_bf16_f32 v52, v28, v2
	v_cvt_pk_bf16_f32 v53, v9, v4
	global_store_dwordx2 v[72:73], v[52:53], off
	s_cbranch_scc1 .LBB0_593
